# chain loop: packed v_pk_mul_f32 between MFMAs split into scalar v_mul_f32 pairs (bit-identical)
# baseline (speedup 1.0000x reference)
.LBB0_503:
	v_mul_f32_e32 v0, v108, v92
	v_mul_f32_e32 v1, v109, v93
	v_mul_f32_e32 v4, v108, v64
	v_mul_f32_e32 v5, v109, v65
	v_mul_f32_e32 v8, v108, v68
	v_mul_f32_e32 v9, v109, v69
	v_mov_b32_e32 v99, v98
	s_waitcnt lgkmcnt(0)
	s_barrier
	s_add_i32 s27, s26, 2
	s_cmp_lt_u32 s26, 31
	s_cselect_b64 s[14:15], -1, 0
	s_and_b64 s[28:29], s[14:15], exec
	s_cselect_b32 s12, s27, 32
	s_add_i32 s30, s12, -2
	s_sub_i32 s12, 33, s12
	s_and_b64 s[28:29], s[2:3], exec
	s_cselect_b32 s12, s30, s12
	s_lshl_b32 s12, s12, 7
	s_add_i32 s12, s12, s16
	v_mad_i64_i32 v[234:235], s[28:29], s12, v129, v[112:113]
	v_lshl_add_u64 v[236:237], v[234:235], 0, s[4:5]
	v_lshl_add_u64 v[238:239], v[234:235], 0, s[8:9]
	v_lshl_add_u64 v[252:253], v[234:235], 0, s[10:11]
	global_load_dwordx4 v[170:173], v[234:235], off offset:1024
	global_load_dwordx4 v[174:177], v[234:235], off offset:2048
	global_load_dwordx4 v[178:181], v[236:237], off offset:1024
	global_load_dwordx4 v[182:185], v[236:237], off offset:2048
	global_load_dwordx4 v[186:189], v[238:239], off offset:1024
	global_load_dwordx4 v[190:193], v[238:239], off offset:2048
	global_load_dwordx4 v[194:197], v[252:253], off offset:1024
	global_load_dwordx4 v[198:201], v[252:253], off offset:2048
	v_mul_f32_e32 v2, v98, v94
	v_mul_f32_e32 v3, v99, v95
	ds_read_b64_tr_b16 v[12:13], v127 offset:1216
	ds_read_b64_tr_b16 v[10:11], v127
	ds_read_b64_tr_b16 v[14:15], v127 offset:32
	ds_read_b64_tr_b16 v[18:19], v127 offset:64
	ds_read_b64_tr_b16 v[22:23], v127 offset:96
	ds_read_b64_tr_b16 v[28:29], v128 offset:1216
	ds_read_b64_tr_b16 v[26:27], v128
	ds_read_b64_tr_b16 v[16:17], v127 offset:1248
	ds_read_b64_tr_b16 v[20:21], v127 offset:1280
	ds_read_b64_tr_b16 v[24:25], v127 offset:1312
	ds_read_b64_tr_b16 v[94:95], v128 offset:1248
	ds_read_b64_tr_b16 v[92:93], v128 offset:32
	v_mul_f32_e32 v6, v98, v66
	v_mul_f32_e32 v7, v99, v67
	s_waitcnt lgkmcnt(5)
	v_mfma_f32_16x16x32_bf16 v[0:3], v[10:13], v[26:29], v[0:3]
	v_mul_f32_e64 v64, v108, v72
	v_mul_f32_e64 v65, v109, v73
	v_mul_f32_e32 v66, v98, v74
	v_mul_f32_e32 v67, v99, v75
	v_mul_f32_e32 v68, v108, v76
	v_mul_f32_e32 v69, v109, v77
	s_waitcnt lgkmcnt(0)
	v_mfma_f32_16x16x32_bf16 v[4:7], v[10:13], v[92:95], v[4:7]
	v_mul_f32_e64 v10, v98, v70
	v_mul_f32_e64 v11, v99, v71
	v_mul_f32_e32 v12, v108, v80
	v_mul_f32_e32 v13, v109, v81
	v_mul_f32_e32 v72, v108, v84
	v_mul_f32_e32 v73, v109, v85
	v_mfma_f32_16x16x32_bf16 v[8:11], v[14:17], v[26:29], v[8:11]
	v_mul_f32_e64 v76, v108, v88
	v_mul_f32_e64 v77, v109, v89
	v_mul_f32_e32 v70, v98, v78
	v_mul_f32_e32 v71, v99, v79
	v_mul_f32_e32 v74, v98, v86
	v_mul_f32_e32 v75, v99, v87
	v_mfma_f32_16x16x32_bf16 v[64:67], v[14:17], v[92:95], v[64:67]
	v_mul_f32_e64 v14, v98, v82
	v_mul_f32_e64 v15, v99, v83
	v_mul_f32_e32 v78, v98, v90
	v_mul_f32_e32 v79, v99, v91
	ds_read_b64_tr_b16 v[16:17], v127 offset:9728
	ds_read_b64_tr_b16 v[80:81], v127 offset:9760
	ds_read_b64_tr_b16 v[84:85], v127 offset:9792
	v_mfma_f32_16x16x32_bf16 v[68:71], v[18:21], v[26:29], v[68:71]
	s_nop 2
	v_mfma_f32_16x16x32_bf16 v[12:15], v[18:21], v[92:95], v[12:15]
	ds_read_b64_tr_b16 v[18:19], v127 offset:10944
	ds_read_b64_tr_b16 v[82:83], v127 offset:10976
	ds_read_b64_tr_b16 v[86:87], v127 offset:11008
	s_nop 1
	v_mfma_f32_16x16x32_bf16 v[26:29], v[22:25], v[26:29], v[72:75]
	ds_read_b64_tr_b16 v[20:21], v127 offset:9824
	s_nop 1
	ds_read_b64_tr_b16 v[72:73], v128 offset:9728
	ds_read_b64_tr_b16 v[74:75], v128 offset:10944
	s_nop 1
	v_mfma_f32_16x16x32_bf16 v[76:79], v[22:25], v[92:95], v[76:79]
	ds_read_b64_tr_b16 v[22:23], v127 offset:11040
	ds_read_b64_tr_b16 v[90:91], v128 offset:10976
	ds_read_b64_tr_b16 v[88:89], v128 offset:9760
	s_nop 1
	s_waitcnt lgkmcnt(3)
	v_mfma_f32_16x16x32_bf16 v[0:3], v[16:19], v[72:75], v[0:3]
	s_nop 1
	s_add_i32 s30, s24, 1
	s_waitcnt lgkmcnt(0)
	v_mfma_f32_16x16x32_bf16 v[4:7], v[16:19], v[88:91], v[4:7]
	v_mov_b32_e32 v115, v97
	v_mov_b32_e32 v117, v97
	v_mfma_f32_16x16x32_bf16 v[16:19], v[80:83], v[88:91], v[64:67]
	s_nop 2
	ds_read_b64_tr_b16 v[64:65], v127 offset:19456
	v_mfma_f32_16x16x32_bf16 v[8:11], v[80:83], v[72:75], v[8:11]
	ds_read_b64_tr_b16 v[66:67], v127 offset:20672
	ds_read_b64_tr_b16 v[82:83], v127 offset:20704
	ds_read_b64_tr_b16 v[94:95], v127 offset:20736
	v_mfma_f32_16x16x32_bf16 v[68:71], v[84:87], v[72:75], v[68:71]
	v_mfma_f32_16x16x32_bf16 v[12:15], v[84:87], v[88:91], v[12:15]
	ds_read_b64_tr_b16 v[80:81], v127 offset:19488
	ds_read_b64_tr_b16 v[92:93], v127 offset:19520
	ds_read_b64_tr_b16 v[84:85], v127 offset:19552
	v_mfma_f32_16x16x32_bf16 v[24:27], v[20:23], v[72:75], v[26:29]
	ds_read_b64_tr_b16 v[86:87], v127 offset:20768
	ds_read_b64_tr_b16 v[72:73], v128 offset:19456
	ds_read_b64_tr_b16 v[74:75], v128 offset:20672
	v_mfma_f32_16x16x32_bf16 v[20:23], v[20:23], v[88:91], v[76:79]
	s_nop 2
	ds_read_b64_tr_b16 v[78:79], v128 offset:20704
	ds_read_b64_tr_b16 v[76:77], v128 offset:19488
	ds_read_b64_tr_b16 v[88:89], v127 offset:29184
	ds_read_b64_tr_b16 v[90:91], v127 offset:30400
	ds_read_b64_tr_b16 v[132:133], v127 offset:30432
	ds_read_b64_tr_b16 v[136:137], v127 offset:30464
	ds_read_b64_tr_b16 v[130:131], v127 offset:29216
	ds_read_b64_tr_b16 v[134:135], v127 offset:29248
	ds_read_b64_tr_b16 v[138:139], v127 offset:29280
	ds_read_b64_tr_b16 v[140:141], v127 offset:30496
	ds_read_b64_tr_b16 v[146:147], v128 offset:29184
	ds_read_b64_tr_b16 v[148:149], v128 offset:30400
	s_waitcnt vmcnt(22)
	v_add_u32_e32 v250, v118, v123
	v_lshlrev_b32_e32 v242, 16, v206
	v_and_b32_e32 v243, 0xffff0000, v206
	v_lshlrev_b32_e32 v244, 16, v207
	v_and_b32_e32 v245, 0xffff0000, v207
	v_lshlrev_b32_e32 v246, 16, v208
	v_and_b32_e32 v247, 0xffff0000, v208
	v_lshlrev_b32_e32 v248, 16, v209
	v_and_b32_e32 v249, 0xffff0000, v209
	v_mul_f32_e32 v242, v100, v242
	v_mul_f32_e32 v243, v101, v243
	v_mul_f32_e32 v244, v100, v244
	v_mul_f32_e32 v245, v101, v245
	v_mul_f32_e32 v246, v100, v246
	v_mul_f32_e32 v247, v101, v247
	v_mul_f32_e32 v248, v100, v248
	v_mul_f32_e32 v249, v101, v249
	v_cvt_pk_bf16_f32 v206, v242, v243
	v_cvt_pk_bf16_f32 v207, v244, v245
	v_cvt_pk_bf16_f32 v208, v246, v247
	v_cvt_pk_bf16_f32 v209, v248, v249
	ds_write_b128 v250, v[202:205]
	ds_write_b128 v250, v[206:209] offset:38912
	s_waitcnt lgkmcnt(14)
	v_mfma_f32_16x16x32_bf16 v[0:3], v[64:67], v[72:75], v[0:3]
	ds_read_b64_tr_b16 v[152:153], v128 offset:30432
	ds_read_b64_tr_b16 v[150:151], v128 offset:29216
	s_waitcnt vmcnt(20)
	v_lshlrev_b32_e32 v242, 16, v214
	v_and_b32_e32 v243, 0xffff0000, v214
	v_lshlrev_b32_e32 v244, 16, v215
	v_and_b32_e32 v245, 0xffff0000, v215
	v_lshlrev_b32_e32 v246, 16, v216
	v_and_b32_e32 v247, 0xffff0000, v216
	v_lshlrev_b32_e32 v248, 16, v217
	v_and_b32_e32 v249, 0xffff0000, v217
	v_mul_f32_e32 v242, v102, v242
	v_mul_f32_e32 v243, v103, v243
	v_mul_f32_e32 v244, v102, v244
	v_mul_f32_e32 v245, v103, v245
	v_mul_f32_e32 v246, v102, v246
	v_mul_f32_e32 v247, v103, v247
	v_mul_f32_e32 v248, v102, v248
	v_mul_f32_e32 v249, v103, v249
	v_cvt_pk_bf16_f32 v214, v242, v243
	v_cvt_pk_bf16_f32 v215, v244, v245
	v_cvt_pk_bf16_f32 v216, v246, v247
	v_cvt_pk_bf16_f32 v217, v248, v249
	ds_write_b128 v250, v[210:213] offset:9728
	ds_write_b128 v250, v[214:217] offset:48640
	s_waitcnt lgkmcnt(15)
	v_mfma_f32_16x16x32_bf16 v[64:67], v[64:67], v[76:79], v[4:7]
	s_nop 2
	v_mfma_f32_16x16x32_bf16 v[142:145], v[80:83], v[72:75], v[8:11]
	s_add_i32 s12, s26, -1
	v_mfma_f32_16x16x32_bf16 v[80:83], v[80:83], v[76:79], v[16:19]
	s_and_b64 s[28:29], s[2:3], exec
	s_cselect_b32 s12, s12, s30
	s_add_i32 s12, s12, s17
	v_mfma_f32_16x16x32_bf16 v[154:157], v[92:95], v[72:75], v[68:71]
	s_lshl_b64 s[28:29], s[12:13], 15
	v_mfma_f32_16x16x32_bf16 v[162:165], v[92:95], v[76:79], v[12:15]
	s_nop 0
	v_mfma_f32_16x16x32_bf16 v[166:169], v[84:87], v[72:75], v[24:27]
	s_nop 2
	v_mfma_f32_16x16x32_bf16 v[84:87], v[84:87], v[76:79], v[20:23]
	s_nop 2
	s_nop 0
	s_nop 0
	s_waitcnt vmcnt(18)
	v_lshlrev_b32_e32 v242, 16, v222
	v_and_b32_e32 v243, 0xffff0000, v222
	v_lshlrev_b32_e32 v244, 16, v223
	v_and_b32_e32 v245, 0xffff0000, v223
	v_lshlrev_b32_e32 v246, 16, v224
	v_and_b32_e32 v247, 0xffff0000, v224
	v_lshlrev_b32_e32 v248, 16, v225
	v_and_b32_e32 v249, 0xffff0000, v225
	v_mul_f32_e32 v242, v104, v242
	v_mul_f32_e32 v243, v105, v243
	v_mul_f32_e32 v244, v104, v244
	v_mul_f32_e32 v245, v105, v245
	v_mul_f32_e32 v246, v104, v246
	v_mul_f32_e32 v247, v105, v247
	v_mul_f32_e32 v248, v104, v248
	v_mul_f32_e32 v249, v105, v249
	v_cvt_pk_bf16_f32 v222, v242, v243
	v_cvt_pk_bf16_f32 v223, v244, v245
	v_cvt_pk_bf16_f32 v224, v246, v247
	v_cvt_pk_bf16_f32 v225, v248, v249
	ds_write_b128 v250, v[218:221] offset:19456
	ds_write_b128 v250, v[222:225] offset:58368
	s_waitcnt lgkmcnt(4)
	v_mfma_f32_16x16x32_bf16 v[92:95], v[88:91], v[146:149], v[0:3]
	s_nop 2
	s_waitcnt vmcnt(16)
	v_lshlrev_b32_e32 v242, 16, v230
	v_and_b32_e32 v243, 0xffff0000, v230
	v_lshlrev_b32_e32 v244, 16, v231
	v_and_b32_e32 v245, 0xffff0000, v231
	v_lshlrev_b32_e32 v246, 16, v232
	v_and_b32_e32 v247, 0xffff0000, v232
	v_lshlrev_b32_e32 v248, 16, v233
	v_and_b32_e32 v249, 0xffff0000, v233
	v_mul_f32_e32 v242, v106, v242
	v_mul_f32_e32 v243, v107, v243
	v_mul_f32_e32 v244, v106, v244
	v_mul_f32_e32 v245, v107, v245
	v_mul_f32_e32 v246, v106, v246
	v_mul_f32_e32 v247, v107, v247
	v_mul_f32_e32 v248, v106, v248
	v_mul_f32_e32 v249, v107, v249
	v_cvt_pk_bf16_f32 v230, v242, v243
	v_cvt_pk_bf16_f32 v231, v244, v245
	v_cvt_pk_bf16_f32 v232, v246, v247
	v_cvt_pk_bf16_f32 v233, v248, v249
	ds_write_b128 v250, v[226:229] offset:29184
	ds_write_b128 v119, v[230:233] offset:58368
	s_waitcnt lgkmcnt(2)
	v_mfma_f32_16x16x32_bf16 v[68:71], v[130:133], v[150:153], v[80:83]
	s_nop 2
	v_lshl_add_u64 v[80:81], v[110:111], 0, s[28:29]
	v_mfma_f32_16x16x32_bf16 v[88:91], v[88:91], v[150:153], v[64:67]
	v_mfma_f32_16x16x32_bf16 v[64:67], v[130:133], v[146:149], v[142:145]
	v_lshl_add_u64 v[130:131], v[80:81], 0, v[96:97]
	v_lshl_add_u64 v[132:133], v[80:81], 0, v[114:115]
	v_mfma_f32_16x16x32_bf16 v[72:75], v[134:137], v[146:149], v[154:157]
	v_cvt_pk_bf16_f32 v144, v68, v69
	s_nop 3
	v_cvt_pk_bf16_f32 v142, v64, v65
	v_cvt_pk_bf16_f32 v143, v66, v67
	v_mfma_f32_16x16x32_bf16 v[76:79], v[134:137], v[150:153], v[162:165]
	v_lshl_add_u64 v[134:135], v[80:81], 0, v[116:117]
	v_add_co_u32_e32 v136, vcc, s25, v130
	v_mfma_f32_16x16x32_bf16 v[80:83], v[138:141], v[146:149], v[166:169]
	s_nop 0
	v_addc_co_u32_e32 v137, vcc, 0, v131, vcc
	v_cvt_pk_bf16_f32 v145, v70, v71
	v_mfma_f32_16x16x32_bf16 v[84:87], v[138:141], v[150:153], v[84:87]
	v_cvt_pk_bf16_f32 v138, v92, v93
	v_cvt_pk_bf16_f32 v139, v94, v95
	v_cvt_pk_bf16_f32 v140, v88, v89
	v_cvt_pk_bf16_f32 v141, v90, v91
	v_cvt_pk_bf16_f32 v146, v72, v73
	v_cvt_pk_bf16_f32 v147, v74, v75
	v_cvt_pk_bf16_f32 v148, v76, v77
	v_cvt_pk_bf16_f32 v149, v78, v79
	v_cvt_pk_bf16_f32 v150, v80, v81
	v_cvt_pk_bf16_f32 v151, v82, v83
	v_cvt_pk_bf16_f32 v152, v84, v85
	v_cvt_pk_bf16_f32 v153, v86, v87
	global_store_dwordx2 v[130:131], v[138:139], off
	global_store_dwordx2 v[136:137], v[140:141], off
	global_store_dwordx2 v[130:131], v[142:143], off offset:512
	global_store_dwordx2 v[132:133], v[144:145], off
	global_store_dwordx2 v[130:131], v[146:147], off offset:1024
	global_store_dwordx2 v[136:137], v[148:149], off offset:1024
	global_store_dwordx2 v[130:131], v[150:151], off offset:1536
	global_store_dwordx2 v[134:135], v[152:153], off
	v_mul_f32_e32 v54, v98, v90
	v_mul_f32_e32 v55, v99, v91
	v_mul_f32_e32 v52, v108, v88
	v_mul_f32_e32 v53, v109, v89
	v_mul_f32_e32 v50, v98, v94
	v_mul_f32_e32 v51, v99, v95
	v_mul_f32_e32 v48, v108, v92
	v_mul_f32_e32 v49, v109, v93
	v_add_u32_e32 v155, v120, v124
	s_waitcnt lgkmcnt(0)
	s_barrier
	s_min_u32 s12, s26, 29
	s_add_i32 s30, s12, 1
	s_sub_i32 s12, 30, s12
	s_and_b64 s[28:29], s[2:3], exec
	s_cselect_b32 s12, s30, s12
	s_lshl_b32 s12, s12, 7
	s_add_i32 s12, s12, s16
	s_mulk_i32 s12, 0x1c00
	v_lshl_add_u64 v[234:235], v[112:113], 0, s[12:13]
	v_lshl_add_u64 v[236:237], v[234:235], 0, s[4:5]
	v_lshl_add_u64 v[238:239], v[234:235], 0, s[8:9]
	v_lshl_add_u64 v[252:253], v[234:235], 0, s[10:11]
	global_load_dwordx4 v[202:205], v[234:235], off offset:1024
	global_load_dwordx4 v[206:209], v[234:235], off offset:2048
	global_load_dwordx4 v[210:213], v[236:237], off offset:1024
	global_load_dwordx4 v[214:217], v[236:237], off offset:2048
	global_load_dwordx4 v[218:221], v[238:239], off offset:1024
	global_load_dwordx4 v[222:225], v[238:239], off offset:2048
	global_load_dwordx4 v[226:229], v[252:253], off offset:1024
	global_load_dwordx4 v[230:233], v[252:253], off offset:2048
	v_add_u32_e32 v156, v121, v124
	ds_read_b64_tr_b16 v[34:35], v155 offset:1216
	ds_read_b64_tr_b16 v[32:33], v155
	ds_read_b64_tr_b16 v[36:37], v155 offset:32
	ds_read_b64_tr_b16 v[40:41], v155 offset:64
	ds_read_b64_tr_b16 v[44:45], v155 offset:96
	ds_read_b64_tr_b16 v[58:59], v156 offset:40128
	ds_read_b64_tr_b16 v[56:57], v156 offset:38912
	ds_read_b64_tr_b16 v[38:39], v155 offset:1248
	ds_read_b64_tr_b16 v[42:43], v155 offset:1280
	ds_read_b64_tr_b16 v[46:47], v155 offset:1312
	ds_read_b64_tr_b16 v[62:63], v156 offset:40160
	ds_read_b64_tr_b16 v[60:61], v156 offset:38944
	v_mul_f32_e32 v66, v98, v66
	v_mul_f32_e32 v67, v99, v67
	v_mul_f32_e32 v64, v108, v64
	v_mul_f32_e32 v65, v109, v65
	v_mul_f32_e32 v70, v98, v70
	v_mul_f32_e32 v71, v99, v71
	v_mul_f32_e32 v68, v108, v68
	v_mul_f32_e32 v69, v109, v69
	s_waitcnt lgkmcnt(5)
	v_mfma_f32_16x16x32_bf16 v[48:51], v[32:35], v[56:59], v[48:51]
	s_nop 2
	s_waitcnt lgkmcnt(0)
	v_mfma_f32_16x16x32_bf16 v[32:35], v[32:35], v[60:63], v[52:55]
	s_nop 2
	v_mul_f32_e32 v54, v98, v74
	v_mul_f32_e32 v55, v99, v75
	v_mul_f32_e32 v52, v108, v72
	v_mul_f32_e32 v53, v109, v73
	v_mfma_f32_16x16x32_bf16 v[64:67], v[36:39], v[56:59], v[64:67]
	v_mul_f32_e64 v74, v98, v78
	v_mul_f32_e64 v75, v99, v79
	v_mul_f32_e32 v72, v108, v76
	v_mul_f32_e32 v73, v109, v77
	v_mul_f32_e32 v78, v98, v82
	v_mul_f32_e32 v79, v99, v83
	v_mfma_f32_16x16x32_bf16 v[36:39], v[36:39], v[60:63], v[68:71]
	v_mul_f32_e64 v76, v108, v80
	v_mul_f32_e64 v77, v109, v81
	s_nop 1
	v_mul_f32_e32 v70, v98, v86
	v_mul_f32_e32 v71, v99, v87
	v_mul_f32_e32 v68, v108, v84
	v_mul_f32_e32 v69, v109, v85
	v_mfma_f32_16x16x32_bf16 v[52:55], v[40:43], v[56:59], v[52:55]
	ds_read_b64_tr_b16 v[80:81], v155 offset:9728
	ds_read_b64_tr_b16 v[84:85], v155 offset:9760
	ds_read_b64_tr_b16 v[88:89], v155 offset:9792
	ds_read_b64_tr_b16 v[82:83], v155 offset:10944
	ds_read_b64_tr_b16 v[86:87], v155 offset:10976
	ds_read_b64_tr_b16 v[90:91], v155 offset:11008
	s_and_b64 s[28:29], s[2:3], exec
	v_mfma_f32_16x16x32_bf16 v[40:43], v[40:43], v[60:63], v[72:75]
	v_mfma_f32_16x16x32_bf16 v[56:59], v[44:47], v[56:59], v[76:79]
	s_nop 1
	ds_read_b64_tr_b16 v[72:73], v155 offset:9824
	ds_read_b64_tr_b16 v[76:77], v156 offset:48640
	ds_read_b64_tr_b16 v[78:79], v156 offset:49856
	v_mfma_f32_16x16x32_bf16 v[44:47], v[44:47], v[60:63], v[68:71]
	ds_read_b64_tr_b16 v[74:75], v155 offset:11040
	ds_read_b64_tr_b16 v[62:63], v156 offset:49888
	ds_read_b64_tr_b16 v[60:61], v156 offset:48672
	s_waitcnt lgkmcnt(3)
	v_mfma_f32_16x16x32_bf16 v[48:51], v[80:83], v[76:79], v[48:51]
	s_waitcnt lgkmcnt(0)
	v_mfma_f32_16x16x32_bf16 v[32:35], v[80:83], v[60:63], v[32:35]
	v_mfma_f32_16x16x32_bf16 v[64:67], v[84:87], v[76:79], v[64:67]
	v_mfma_f32_16x16x32_bf16 v[36:39], v[84:87], v[60:63], v[36:39]
	ds_read_b64_tr_b16 v[68:69], v155 offset:19456
	ds_read_b64_tr_b16 v[80:81], v155 offset:19488
	ds_read_b64_tr_b16 v[84:85], v155 offset:19520
	ds_read_b64_tr_b16 v[70:71], v155 offset:20672
	ds_read_b64_tr_b16 v[82:83], v155 offset:20704
	ds_read_b64_tr_b16 v[86:87], v155 offset:20736
	v_mfma_f32_16x16x32_bf16 v[52:55], v[88:91], v[76:79], v[52:55]
	v_mfma_f32_16x16x32_bf16 v[40:43], v[88:91], v[60:63], v[40:43]
	v_mfma_f32_16x16x32_bf16 v[56:59], v[72:75], v[76:79], v[56:59]
	ds_read_b64_tr_b16 v[76:77], v155 offset:19552
	ds_read_b64_tr_b16 v[88:89], v156 offset:58368
	ds_read_b64_tr_b16 v[90:91], v156 offset:59584
	v_mfma_f32_16x16x32_bf16 v[44:47], v[72:75], v[60:63], v[44:47]
	ds_read_b64_tr_b16 v[78:79], v155 offset:20768
	ds_read_b64_tr_b16 v[62:63], v156 offset:59616
	ds_read_b64_tr_b16 v[60:61], v156 offset:58400
	s_waitcnt vmcnt(22)
	v_lshlrev_b32_e32 v242, 16, v174
	v_and_b32_e32 v243, 0xffff0000, v174
	v_lshlrev_b32_e32 v244, 16, v175
	v_and_b32_e32 v245, 0xffff0000, v175
	v_lshlrev_b32_e32 v246, 16, v176
	v_and_b32_e32 v247, 0xffff0000, v176
	v_lshlrev_b32_e32 v248, 16, v177
	v_and_b32_e32 v249, 0xffff0000, v177
	v_mul_f32_e32 v242, v100, v242
	v_mul_f32_e32 v243, v101, v243
	v_mul_f32_e32 v244, v100, v244
	v_mul_f32_e32 v245, v101, v245
	v_mul_f32_e32 v246, v100, v246
	v_mul_f32_e32 v247, v101, v247
	v_mul_f32_e32 v248, v100, v248
	v_mul_f32_e32 v249, v101, v249
	v_cvt_pk_bf16_f32 v174, v242, v243
	v_cvt_pk_bf16_f32 v175, v244, v245
	v_cvt_pk_bf16_f32 v176, v246, v247
	v_cvt_pk_bf16_f32 v177, v248, v249
	ds_write_b128 v125, v[170:173]
	ds_write_b128 v126, v[174:177]
	s_waitcnt lgkmcnt(5)
	v_mfma_f32_16x16x32_bf16 v[72:75], v[80:83], v[88:91], v[64:67]
	s_waitcnt vmcnt(20)
	v_lshlrev_b32_e32 v242, 16, v182
	v_and_b32_e32 v243, 0xffff0000, v182
	v_lshlrev_b32_e32 v244, 16, v183
	v_and_b32_e32 v245, 0xffff0000, v183
	v_lshlrev_b32_e32 v246, 16, v184
	v_and_b32_e32 v247, 0xffff0000, v184
	v_lshlrev_b32_e32 v248, 16, v185
	v_and_b32_e32 v249, 0xffff0000, v185
	v_mul_f32_e32 v242, v102, v242
	v_mul_f32_e32 v243, v103, v243
	v_mul_f32_e32 v244, v102, v244
	v_mul_f32_e32 v245, v103, v245
	v_mul_f32_e32 v246, v102, v246
	v_mul_f32_e32 v247, v103, v247
	v_mul_f32_e32 v248, v102, v248
	v_mul_f32_e32 v249, v103, v249
	v_cvt_pk_bf16_f32 v182, v242, v243
	v_cvt_pk_bf16_f32 v183, v244, v245
	v_cvt_pk_bf16_f32 v184, v246, v247
	v_cvt_pk_bf16_f32 v185, v248, v249
	ds_write_b128 v125, v[178:181] offset:9728
	ds_write_b128 v126, v[182:185] offset:9728
	s_waitcnt lgkmcnt(4)
	v_mfma_f32_16x16x32_bf16 v[80:83], v[80:83], v[60:63], v[36:39]
	s_nop 2
	ds_read_b64_tr_b16 v[36:37], v155 offset:29184
	ds_read_b64_tr_b16 v[38:39], v155 offset:30400
	ds_read_b64_tr_b16 v[132:133], v155 offset:30432
	ds_read_b64_tr_b16 v[130:131], v155 offset:29216
	ds_read_b64_tr_b16 v[138:139], v155 offset:29248
	ds_read_b64_tr_b16 v[142:143], v155 offset:29280
	ds_read_b64_tr_b16 v[140:141], v155 offset:30464
	ds_read_b64_tr_b16 v[144:145], v155 offset:30496
	ds_read_b64_tr_b16 v[148:149], v122 offset:40128
	ds_read_b64_tr_b16 v[146:147], v122 offset:38912
	ds_read_b64_tr_b16 v[152:153], v122 offset:40160
	ds_read_b64_tr_b16 v[150:151], v122 offset:38944
	v_mfma_f32_16x16x32_bf16 v[48:51], v[68:71], v[88:91], v[48:51]
	v_mfma_f32_16x16x32_bf16 v[68:71], v[68:71], v[60:63], v[32:35]
	v_mfma_f32_16x16x32_bf16 v[134:137], v[84:87], v[88:91], v[52:55]
	v_mfma_f32_16x16x32_bf16 v[84:87], v[84:87], v[60:63], v[40:43]
	s_nop 2
	v_mfma_f32_16x16x32_bf16 v[154:157], v[76:79], v[60:63], v[44:47]
	v_mfma_f32_16x16x32_bf16 v[88:91], v[76:79], v[88:91], v[56:59]
	s_cselect_b32 s12, s26, s24
	s_add_i32 s12, s12, s17
	s_lshl_b64 s[28:29], s[12:13], 15
	s_waitcnt vmcnt(18)
	v_lshlrev_b32_e32 v242, 16, v190
	v_and_b32_e32 v243, 0xffff0000, v190
	v_lshlrev_b32_e32 v244, 16, v191
	v_and_b32_e32 v245, 0xffff0000, v191
	v_lshlrev_b32_e32 v246, 16, v192
	v_and_b32_e32 v247, 0xffff0000, v192
	v_lshlrev_b32_e32 v248, 16, v193
	v_and_b32_e32 v249, 0xffff0000, v193
	v_mul_f32_e32 v242, v104, v242
	v_mul_f32_e32 v243, v105, v243
	v_mul_f32_e32 v244, v104, v244
	v_mul_f32_e32 v245, v105, v245
	v_mul_f32_e32 v246, v104, v246
	v_mul_f32_e32 v247, v105, v247
	v_mul_f32_e32 v248, v104, v248
	v_mul_f32_e32 v249, v105, v249
	v_cvt_pk_bf16_f32 v190, v242, v243
	v_cvt_pk_bf16_f32 v191, v244, v245
	v_cvt_pk_bf16_f32 v192, v246, v247
	v_cvt_pk_bf16_f32 v193, v248, v249
	ds_write_b128 v125, v[186:189] offset:19456
	ds_write_b128 v126, v[190:193] offset:19456
	s_waitcnt lgkmcnt(4)
	v_mfma_f32_16x16x32_bf16 v[92:95], v[36:39], v[146:149], v[48:51]
	s_waitcnt vmcnt(16)
	v_lshlrev_b32_e32 v242, 16, v198
	v_and_b32_e32 v243, 0xffff0000, v198
	v_lshlrev_b32_e32 v244, 16, v199
	v_and_b32_e32 v245, 0xffff0000, v199
	v_lshlrev_b32_e32 v246, 16, v200
	v_and_b32_e32 v247, 0xffff0000, v200
	v_lshlrev_b32_e32 v248, 16, v201
	v_and_b32_e32 v249, 0xffff0000, v201
	v_mul_f32_e32 v242, v106, v242
	v_mul_f32_e32 v243, v107, v243
	v_mul_f32_e32 v244, v106, v244
	v_mul_f32_e32 v245, v107, v245
	v_mul_f32_e32 v246, v106, v246
	v_mul_f32_e32 v247, v107, v247
	v_mul_f32_e32 v248, v106, v248
	v_mul_f32_e32 v249, v107, v249
	v_cvt_pk_bf16_f32 v198, v242, v243
	v_cvt_pk_bf16_f32 v199, v244, v245
	v_cvt_pk_bf16_f32 v200, v246, v247
	v_cvt_pk_bf16_f32 v201, v248, v249
	ds_write_b128 v125, v[194:197] offset:29184
	ds_write_b128 v126, v[198:201] offset:29184
	s_waitcnt lgkmcnt(2)
	v_mfma_f32_16x16x32_bf16 v[64:67], v[36:39], v[150:153], v[68:71]
	s_nop 0
	s_nop 0
	s_nop 0
	v_mfma_f32_16x16x32_bf16 v[68:71], v[130:133], v[146:149], v[72:75]
	v_mfma_f32_16x16x32_bf16 v[72:75], v[130:133], v[150:153], v[80:83]
	v_lshl_add_u64 v[130:131], v[110:111], 0, s[28:29]
	v_lshl_add_u64 v[132:133], v[130:131], 0, v[96:97]
	v_mfma_f32_16x16x32_bf16 v[76:79], v[138:141], v[146:149], v[134:137]
	v_mfma_f32_16x16x32_bf16 v[80:83], v[138:141], v[150:153], v[84:87]
	s_nop 1
	v_add_co_u32_e32 v136, vcc, s25, v132
	v_cvt_pk_bf16_f32 v138, v92, v93
	v_mfma_f32_16x16x32_bf16 v[84:87], v[142:145], v[146:149], v[88:91]
	v_cvt_pk_bf16_f32 v139, v94, v95
	v_lshl_add_u64 v[134:135], v[130:131], 0, v[114:115]
	v_lshl_add_u64 v[130:131], v[130:131], 0, v[116:117]
	v_mfma_f32_16x16x32_bf16 v[88:91], v[142:145], v[150:153], v[154:157]
	v_addc_co_u32_e32 v137, vcc, 0, v133, vcc
	v_cvt_pk_bf16_f32 v140, v64, v65
	v_cvt_pk_bf16_f32 v141, v66, v67
	v_cvt_pk_bf16_f32 v142, v68, v69
	v_cvt_pk_bf16_f32 v143, v70, v71
	v_cvt_pk_bf16_f32 v144, v72, v73
	v_cvt_pk_bf16_f32 v145, v74, v75
	v_cvt_pk_bf16_f32 v146, v76, v77
	v_cvt_pk_bf16_f32 v147, v78, v79
	v_cvt_pk_bf16_f32 v148, v80, v81
	v_cvt_pk_bf16_f32 v149, v82, v83
	v_cvt_pk_bf16_f32 v150, v84, v85
	v_cvt_pk_bf16_f32 v151, v86, v87
	v_cvt_pk_bf16_f32 v152, v88, v89
	v_cvt_pk_bf16_f32 v153, v90, v91
	global_store_dwordx2 v[132:133], v[138:139], off
	global_store_dwordx2 v[136:137], v[140:141], off
	global_store_dwordx2 v[132:133], v[142:143], off offset:512
	global_store_dwordx2 v[134:135], v[144:145], off
	global_store_dwordx2 v[132:133], v[146:147], off offset:1024
	global_store_dwordx2 v[136:137], v[148:149], off offset:1024
	global_store_dwordx2 v[132:133], v[150:151], off offset:1536
	global_store_dwordx2 v[130:131], v[152:153], off
	s_add_i32 s24, s24, -2
	s_and_b64 vcc, exec, s[14:15]
	s_mov_b32 s26, s27
	s_cbranch_vccnz .LBB0_503
	s_waitcnt lgkmcnt(0)
	s_barrier
